# attention L0 main loop: PV MFMAs issued as two 4-long accumulate chains (o0 x4, o1 x4) instead of alternating
# baseline (speedup 1.0000x reference)
.LBB0_615:
	s_mov_b32 s62, s60
	s_mov_b32 s60, s56
	s_mov_b32 s58, s66
	s_mov_b64 s[22:23], s[44:45]
	s_mov_b32 s59, s65
	v_add_u32_e32 v148, s64, v167
	ds_read_b64_tr_b16 v[140:141], v148 offset:32768
	ds_read_b64_tr_b16 v[142:143], v148 offset:33280
	s_add_i32 s14, s63, 0xffffe000
	s_and_b32 s44, s14, 0x6000
	v_add_u32_e32 v96, s44, v164
	s_waitcnt lgkmcnt(2)
	v_mfma_f32_32x32x16_bf16 v[80:95], v[80:83], v[124:127], 0
	v_add_f32_e32 v64, v48, v49
	v_add_f32_e32 v64, v50, v64
	v_add_f32_e32 v64, v51, v64
	v_add_f32_e32 v64, v52, v64
	v_add_f32_e32 v64, v53, v64
	v_cvt_pk_bf16_f32 v108, v48, v49
	v_cvt_pk_bf16_f32 v109, v50, v51
	ds_read_b64_tr_b16 v[48:49], v148 offset:36864
	ds_read_b64_tr_b16 v[50:51], v148 offset:37376
	v_add_f32_e32 v64, v54, v64
	v_add_f32_e32 v64, v55, v64
	v_add_f32_e32 v64, v56, v64
	v_add_f32_e32 v97, v57, v64
	v_cvt_pk_bf16_f32 v110, v52, v53
	v_cvt_pk_bf16_f32 v111, v54, v55
	v_mfma_f32_32x32x16_bf16 v[64:79], v[136:139], v[124:127], 0
	ds_read_b128 v[52:55], v96 offset:4096
	ds_read_b128 v[136:139], v96 offset:4608
	ds_read_b64_tr_b16 v[144:145], v148 offset:33792
	ds_read_b64_tr_b16 v[146:147], v148 offset:34304
	v_mfma_f32_32x32x16_bf16 v[80:95], v[132:135], v[120:123], v[80:95]
	v_add_f32_e32 v97, v58, v97
	v_add_f32_e32 v97, v59, v97
	v_add_f32_e32 v97, v60, v97
	v_add_f32_e32 v97, v61, v97
	v_cvt_pk_bf16_f32 v104, v56, v57
	v_cvt_pk_bf16_f32 v105, v58, v59
	ds_read_b64_tr_b16 v[56:57], v148 offset:37888
	ds_read_b64_tr_b16 v[58:59], v148 offset:38400
	v_add_f32_e32 v97, v62, v97
	v_add_f32_e32 v97, v63, v97
	v_add_f32_e32 v97, v32, v97
	v_add_f32_e32 v97, v33, v97
	v_cvt_pk_bf16_f32 v106, v60, v61
	v_cvt_pk_bf16_f32 v107, v62, v63
	v_mfma_f32_32x32x16_bf16 v[64:79], v[128:131], v[120:123], v[64:79]
	ds_read_b128 v[60:63], v96 offset:6144
	ds_read_b128 v[128:131], v96 offset:6656
	ds_read_b64_tr_b16 v[132:133], v148 offset:34816
	ds_read_b64_tr_b16 v[134:135], v148 offset:35328
	s_waitcnt lgkmcnt(9)
	v_mfma_f32_32x32x16_bf16 v[80:95], v[52:55], v[116:119], v[80:95]
	v_add_f32_e32 v96, v34, v97
	v_add_f32_e32 v96, v35, v96
	v_add_f32_e32 v96, v36, v96
	v_add_f32_e32 v96, v37, v96
	v_cvt_pk_bf16_f32 v100, v32, v33
	v_cvt_pk_bf16_f32 v101, v34, v35
	ds_read_b64_tr_b16 v[32:33], v148 offset:38912
	ds_read_b64_tr_b16 v[34:35], v148 offset:39424
	v_add_f32_e32 v52, v38, v96
	v_add_f32_e32 v52, v39, v52
	v_add_f32_e32 v52, v40, v52
	v_add_f32_e32 v52, v41, v52
	v_cvt_pk_bf16_f32 v102, v36, v37
	v_cvt_pk_bf16_f32 v103, v38, v39
	s_waitcnt lgkmcnt(10)
	v_mfma_f32_32x32x16_bf16 v[64:79], v[136:139], v[116:119], v[64:79]
	ds_read_b64_tr_b16 v[36:37], v148 offset:35840
	ds_read_b64_tr_b16 v[38:39], v148 offset:36352
	s_waitcnt lgkmcnt(7)
	v_mfma_f32_32x32x16_bf16 v[80:95], v[60:63], v[112:115], v[80:95]
	v_add_f32_e32 v52, v42, v52
	v_add_f32_e32 v52, v43, v52
	v_add_f32_e32 v52, v44, v52
	v_add_f32_e32 v52, v45, v52
	v_cvt_pk_bf16_f32 v96, v40, v41
	v_cvt_pk_bf16_f32 v97, v42, v43
	ds_read_b64_tr_b16 v[40:41], v148 offset:39936
	ds_read_b64_tr_b16 v[42:43], v148 offset:40448
	v_add_f32_e32 v52, v46, v52
	v_add_f32_e32 v52, v47, v52
	v_add_f32_e32 v52, 0, v52
	v_cvt_pk_bf16_f32 v98, v44, v45
	v_cvt_pk_bf16_f32 v99, v46, v47
	s_waitcnt lgkmcnt(8)
	v_mfma_f32_32x32x16_bf16 v[64:79], v[128:131], v[112:115], v[64:79]
	s_add_u32 s34, s42, 0xffff8000
	s_addc_u32 s35, s43, -1
	s_add_i32 s64, s63, 0x4000
	s_and_b32 s14, s64, 0x6000
	s_add_i32 s14, s14, s54
	s_mov_b32 m0, s14
	s_nop 0
	global_load_lds_dwordx4 v169, s[34:35]
	s_add_u32 s34, s40, 0xffff8000
	s_addc_u32 s35, s41, -1
	s_add_i32 s14, s62, s55
	s_mov_b32 m0, s14
	s_nop 0
	global_load_lds_dwordx4 v170, s[34:35]
	v_add_f32_e32 v148, v168, v52
	v_mfma_f32_32x32x16_bf16 v[0:15], v[108:111], v[140:143], v[0:15]
	v_exp_f32_e32 v80, v80
	v_exp_f32_e32 v81, v81
	v_exp_f32_e32 v82, v82
	v_exp_f32_e32 v83, v83
	s_waitcnt lgkmcnt(12)
	v_mfma_f32_32x32x16_bf16 v[0:15], v[104:107], v[144:147], v[0:15]
	v_exp_f32_e32 v84, v84
	v_exp_f32_e32 v85, v85
	v_exp_f32_e32 v86, v86
	v_exp_f32_e32 v87, v87
	s_waitcnt lgkmcnt(6)
	v_mfma_f32_32x32x16_bf16 v[0:15], v[100:103], v[132:135], v[0:15]
	v_exp_f32_e32 v88, v88
	v_exp_f32_e32 v89, v89
	v_exp_f32_e32 v90, v90
	v_exp_f32_e32 v91, v91
	s_waitcnt lgkmcnt(2)
	v_mfma_f32_32x32x16_bf16 v[0:15], v[96:99], v[36:39], v[0:15]
	v_exp_f32_e32 v92, v92
	v_exp_f32_e32 v93, v93
	v_exp_f32_e32 v94, v94
	v_exp_f32_e32 v95, v95
	v_mfma_f32_32x32x16_bf16 v[16:31], v[108:111], v[48:51], v[16:31]
	v_exp_f32_e32 v64, v64
	v_exp_f32_e32 v65, v65
	v_exp_f32_e32 v66, v66
	v_exp_f32_e32 v67, v67
	s_and_b32 s14, s63, 0x6000
	v_add_u32_e32 v149, s14, v164
	ds_read_b128 v[44:47], v149
	ds_read_b128 v[128:131], v149 offset:512
	ds_read_b128 v[136:139], v149 offset:2048
	ds_read_b128 v[140:143], v149 offset:2560
	v_mfma_f32_32x32x16_bf16 v[16:31], v[104:107], v[56:59], v[16:31]
	v_exp_f32_e32 v68, v68
	v_exp_f32_e32 v69, v69
	v_exp_f32_e32 v70, v70
	v_exp_f32_e32 v71, v71
	v_mfma_f32_32x32x16_bf16 v[16:31], v[100:103], v[32:35], v[16:31]
	v_exp_f32_e32 v72, v72
	v_exp_f32_e32 v73, v73
	v_exp_f32_e32 v74, v74
	v_exp_f32_e32 v75, v75
	s_waitcnt lgkmcnt(4)
	v_mfma_f32_32x32x16_bf16 v[16:31], v[96:99], v[40:43], v[16:31]
	v_exp_f32_e32 v76, v76
	v_exp_f32_e32 v77, v77
	v_exp_f32_e32 v78, v78
	v_exp_f32_e32 v79, v79
	s_waitcnt vmcnt(2) lgkmcnt(0)
	s_barrier
	s_add_i32 s14, s62, 0x2000
	s_cmpk_lg_i32 s62, 0x4000
	s_cselect_b32 s56, s14, 0
	v_add_u32_e32 v150, s60, v167
	ds_read_b64_tr_b16 v[132:133], v150 offset:32768
	ds_read_b64_tr_b16 v[134:135], v150 offset:33280
	s_waitcnt lgkmcnt(5)
	v_mfma_f32_32x32x16_bf16 v[48:63], v[44:47], v[124:127], 0
	v_add_f32_e32 v32, v80, v81
	v_add_f32_e32 v32, v82, v32
	v_add_f32_e32 v32, v83, v32
	v_add_f32_e32 v32, v84, v32
	v_add_f32_e32 v32, v85, v32
	v_cvt_pk_bf16_f32 v108, v80, v81
	v_cvt_pk_bf16_f32 v109, v82, v83
	ds_read_b64_tr_b16 v[80:81], v150 offset:36864
	ds_read_b64_tr_b16 v[82:83], v150 offset:37376
	v_add_f32_e32 v32, v86, v32
	v_add_f32_e32 v32, v87, v32
	v_add_f32_e32 v32, v88, v32
	v_add_f32_e32 v96, v89, v32
	s_waitcnt lgkmcnt(6)
	v_mfma_f32_32x32x16_bf16 v[32:47], v[128:131], v[124:127], 0
	v_cvt_pk_bf16_f32 v110, v84, v85
	v_cvt_pk_bf16_f32 v111, v86, v87
	ds_read_b128 v[84:87], v149 offset:4096
	ds_read_b128 v[128:131], v149 offset:4608
	ds_read_b64_tr_b16 v[144:145], v150 offset:33792
	ds_read_b64_tr_b16 v[146:147], v150 offset:34304
	s_waitcnt lgkmcnt(9)
	v_mfma_f32_32x32x16_bf16 v[48:63], v[136:139], v[120:123], v[48:63]
	v_add_f32_e32 v96, v90, v96
	v_add_f32_e32 v96, v91, v96
	v_add_f32_e32 v96, v92, v96
	v_add_f32_e32 v96, v93, v96
	v_cvt_pk_bf16_f32 v104, v88, v89
	v_cvt_pk_bf16_f32 v105, v90, v91
	ds_read_b64_tr_b16 v[88:89], v150 offset:37888
	ds_read_b64_tr_b16 v[90:91], v150 offset:38400
	s_waitcnt lgkmcnt(10)
	v_mfma_f32_32x32x16_bf16 v[32:47], v[140:143], v[120:123], v[32:47]
	v_add_f32_e32 v96, v94, v96
	v_add_f32_e32 v96, v95, v96
	v_add_f32_e32 v96, v64, v96
	v_add_f32_e32 v96, v65, v96
	v_cvt_pk_bf16_f32 v106, v92, v93
	v_cvt_pk_bf16_f32 v107, v94, v95
	ds_read_b128 v[92:95], v149 offset:6144
	ds_read_b128 v[136:139], v149 offset:6656
	ds_read_b64_tr_b16 v[140:141], v150 offset:34816
	ds_read_b64_tr_b16 v[142:143], v150 offset:35328
	s_waitcnt lgkmcnt(9)
	v_mfma_f32_32x32x16_bf16 v[48:63], v[84:87], v[116:119], v[48:63]
	v_add_f32_e32 v96, v66, v96
	v_add_f32_e32 v96, v67, v96
	v_add_f32_e32 v96, v68, v96
	v_add_f32_e32 v96, v69, v96
	v_cvt_pk_bf16_f32 v100, v64, v65
	v_cvt_pk_bf16_f32 v101, v66, v67
	ds_read_b64_tr_b16 v[64:65], v150 offset:38912
	ds_read_b64_tr_b16 v[66:67], v150 offset:39424
	s_waitcnt lgkmcnt(10)
	v_mfma_f32_32x32x16_bf16 v[32:47], v[128:131], v[116:119], v[32:47]
	v_add_f32_e32 v84, v70, v96
	v_add_f32_e32 v84, v71, v84
	v_add_f32_e32 v84, v72, v84
	v_add_f32_e32 v84, v73, v84
	v_cvt_pk_bf16_f32 v102, v68, v69
	v_cvt_pk_bf16_f32 v103, v70, v71
	ds_read_b64_tr_b16 v[68:69], v150 offset:35840
	ds_read_b64_tr_b16 v[70:71], v150 offset:36352
	s_waitcnt lgkmcnt(7)
	v_mfma_f32_32x32x16_bf16 v[48:63], v[92:95], v[112:115], v[48:63]
	v_add_f32_e32 v84, v74, v84
	v_add_f32_e32 v84, v75, v84
	v_add_f32_e32 v84, v76, v84
	v_add_f32_e32 v84, v77, v84
	v_cvt_pk_bf16_f32 v96, v72, v73
	v_cvt_pk_bf16_f32 v97, v74, v75
	ds_read_b64_tr_b16 v[72:73], v150 offset:39936
	ds_read_b64_tr_b16 v[74:75], v150 offset:40448
	s_waitcnt lgkmcnt(8)
	v_mfma_f32_32x32x16_bf16 v[32:47], v[136:139], v[112:115], v[32:47]
	v_add_f32_e32 v84, v78, v84
	v_add_f32_e32 v84, v79, v84
	v_add_f32_e32 v84, 0, v84
	v_cvt_pk_bf16_f32 v98, v76, v77
	v_cvt_pk_bf16_f32 v99, v78, v79
	s_add_i32 s14, s44, s54
	s_mov_b32 m0, s14
	s_nop 0
	global_load_lds_dwordx4 v169, s[42:43]
	s_add_i32 s14, s56, s55
	s_mov_b32 m0, s14
	s_nop 0
	global_load_lds_dwordx4 v170, s[40:41]
	v_add_f32_e32 v168, v148, v84
	s_add_i32 s57, s57, 2
	v_mfma_f32_32x32x16_bf16 v[0:15], v[108:111], v[132:135], v[0:15]
	v_exp_f32_e32 v48, v48
	v_exp_f32_e32 v49, v49
	v_exp_f32_e32 v50, v50
	v_exp_f32_e32 v51, v51
	s_waitcnt lgkmcnt(12)
	v_mfma_f32_32x32x16_bf16 v[0:15], v[104:107], v[144:147], v[0:15]
	v_exp_f32_e32 v52, v52
	v_exp_f32_e32 v53, v53
	v_exp_f32_e32 v54, v54
	v_exp_f32_e32 v55, v55
	s_waitcnt lgkmcnt(6)
	v_mfma_f32_32x32x16_bf16 v[0:15], v[100:103], v[140:143], v[0:15]
	v_exp_f32_e32 v56, v56
	v_exp_f32_e32 v57, v57
	v_exp_f32_e32 v58, v58
	v_exp_f32_e32 v59, v59
	s_waitcnt lgkmcnt(2)
	v_mfma_f32_32x32x16_bf16 v[0:15], v[96:99], v[68:71], v[0:15]
	v_exp_f32_e32 v60, v60
	v_exp_f32_e32 v61, v61
	v_exp_f32_e32 v62, v62
	v_exp_f32_e32 v63, v63
	v_mfma_f32_32x32x16_bf16 v[16:31], v[108:111], v[80:83], v[16:31]
	v_exp_f32_e32 v32, v32
	v_exp_f32_e32 v33, v33
	v_exp_f32_e32 v34, v34
	v_exp_f32_e32 v35, v35
	s_add_i32 s14, s63, 0x2000
	s_and_b32 s14, s14, 0x6000
	v_add_u32_e32 v76, s14, v164
	ds_read_b128 v[80:83], v76
	ds_read_b128 v[136:139], v76 offset:512
	ds_read_b128 v[132:135], v76 offset:2048
	ds_read_b128 v[128:131], v76 offset:2560
	v_mfma_f32_32x32x16_bf16 v[16:31], v[104:107], v[88:91], v[16:31]
	v_exp_f32_e32 v36, v36
	v_exp_f32_e32 v37, v37
	v_exp_f32_e32 v38, v38
	v_exp_f32_e32 v39, v39
	v_mfma_f32_32x32x16_bf16 v[16:31], v[100:103], v[64:67], v[16:31]
	v_exp_f32_e32 v40, v40
	v_exp_f32_e32 v41, v41
	v_exp_f32_e32 v42, v42
	v_exp_f32_e32 v43, v43
	s_waitcnt lgkmcnt(4)
	v_mfma_f32_32x32x16_bf16 v[16:31], v[96:99], v[72:75], v[16:31]
	v_exp_f32_e32 v44, v44
	v_exp_f32_e32 v45, v45
	v_exp_f32_e32 v46, v46
	v_exp_f32_e32 v47, v47
	s_add_i32 s14, s56, 0x2000
	s_cmpk_lg_i32 s56, 0x4000
	s_cselect_b32 s60, s14, 0
	s_add_u32 s40, s40, 0x10000
	s_addc_u32 s41, s41, 0
	s_add_u32 s42, s42, 0x10000
	s_addc_u32 s43, s43, 0
	s_addk_i32 s66, 0x4000
	s_waitcnt vmcnt(2) lgkmcnt(0)
	s_barrier
	s_add_u32 s44, s22, 0x10000
	s_addc_u32 s45, s23, 0
	s_add_i32 s65, s65, 2
	s_cmp_ge_u32 s57, s61
	s_mov_b32 s63, s64
	s_mov_b32 s64, s62
	s_cbranch_scc0 .LBB0_615
	s_add_i32 s14, s57, 1
	s_cmp_ge_u32 s14, s53
	s_cbranch_scc1 .LBB0_644
	s_add_i32 s61, s53, -2
